# G1 layer 1: the 8 per-row statistics of a unit are loaded one unit ahead, so the input-projection epilogue starts without a load round trip
# baseline (speedup 1.0000x reference)
.LBB0_190:
	s_lshl_b32 s59, s0, 6
	s_lshl_b32 s8, s0, 13
	s_lshl_b32 s0, s1, 5
	s_and_b32 s9, s0, 0x60
	s_add_i32 m0, s18, 0x18000
	v_lshl_add_u64 v[6:7], v[6:7], 0, s[76:77]
	s_lshl_b32 s23, s9, 7
	s_waitcnt vmcnt(4)
	s_barrier
	global_load_lds_dwordx4 v[6:7], off
	v_lshl_add_u64 v[4:5], v[4:5], 0, s[76:77]
	s_add_i32 m0, s18, 0x1a000
	s_add_i32 s60, s18, 0x8000
	s_add_i32 s61, s18, 0xa000
	global_load_lds_dwordx4 v[4:5], off
	v_lshl_add_u64 v[2:3], v[2:3], 0, s[76:77]
	s_mov_b32 m0, s60
	s_add_u32 s0, s42, 0x40080
	global_load_lds_dwordx4 v[2:3], off
	v_lshl_add_u64 v[0:1], v[0:1], 0, s[76:77]
	s_mov_b32 m0, s61
	s_addc_u32 s1, s43, 0
	global_load_lds_dwordx4 v[0:1], off
	s_add_i32 m0, s18, 0x1c000
	v_lshl_add_u64 v[0:1], s[0:1], 0, v[172:173]
	global_load_lds_dwordx4 v[0:1], off
	v_lshl_add_u64 v[0:1], s[0:1], 0, v[132:133]
	s_add_i32 m0, s18, 0x1e000
	v_bfe_u32 v145, v8, 4, 2
	global_load_lds_dwordx4 v[0:1], off
	v_and_b32_e32 v144, 15, v8
	v_lshlrev_b32_e32 v0, 4, v145
	v_lshlrev_b32_e32 v1, 2, v8
	v_lshl_or_b32 v0, v144, 6, v0
	v_and_b32_e32 v1, 32, v1
	s_lshl_b32 s0, s9, 1
	v_bitop3_b32 v2, v0, s8, v1 bitop3:0xde
	s_add_u32 s8, s86, s0
	s_waitcnt vmcnt(6)
	s_addc_u32 s9, s87, 0
	s_and_b64 s[0:1], s[78:79], exec
	v_bitop3_b32 v146, v0, s23, v1 bitop3:0xde
	s_cselect_b32 s62, 20, 19
	s_mov_b32 s63, 0
	v_lshl_add_u64 v[134:135], s[54:55], 0, v[130:131]
	v_lshl_add_u64 v[136:137], s[54:55], 0, v[128:129]
	v_add_u32_e32 v147, 0, v2
	s_mov_b64 s[68:69], s[40:41]
	s_mov_b64 s[34:35], s[42:43]
	s_barrier
	v_readlane_b32 s0, v234, 57
	s_nop 3
	s_cmp_eq_u32 s0, 0
	s_cbranch_scc1 .Lmy_rs_skip_first
	s_lshl_b32 s0, s22, 8
	s_add_i32 s0, s0, s59
	v_add_u32_e32 v238, s0, v144
	v_ashrrev_i32_e32 v239, 31, v238
	v_lshl_add_u64 v[238:239], v[238:239], 2, s[64:65]
	global_load_dword v240, v[238:239], off
	global_load_dword v241, v[238:239], off offset:64
	global_load_dword v242, v[238:239], off offset:128
	global_load_dword v243, v[238:239], off offset:192
	global_load_dword v244, v[238:239], off offset:512
	global_load_dword v245, v[238:239], off offset:576
	global_load_dword v246, v[238:239], off offset:640
	global_load_dword v247, v[238:239], off offset:704
.Lmy_rs_skip_first:
	s_nop 0
	s_nop 0
	s_nop 0
	s_nop 0
	s_nop 0
	s_nop 0
	s_nop 0
	s_nop 0
	s_nop 0
	s_nop 0
	s_branch .LBB0_192
.LBB0_191:
	s_and_b64 vcc, exec, s[46:47]
	s_mov_b32 s70, s97
	s_mov_b32 s22, s48
	s_mov_b64 s[42:43], s[34:35]
	s_mov_b64 s[40:41], s[68:69]
	s_cbranch_vccnz .LBB0_248
	v_readlane_b32 s0, v234, 57
	s_nop 3
	s_cmp_eq_u32 s0, 0
	s_cbranch_scc1 .Lmy_rs_skip_next
	s_lshl_b32 s0, s22, 8
	s_add_i32 s0, s0, s59
	v_add_u32_e32 v238, s0, v144
	v_ashrrev_i32_e32 v239, 31, v238
	v_lshl_add_u64 v[238:239], v[238:239], 2, s[64:65]
	global_load_dword v240, v[238:239], off
	global_load_dword v241, v[238:239], off offset:64
	global_load_dword v242, v[238:239], off offset:128
	global_load_dword v243, v[238:239], off offset:192
	global_load_dword v244, v[238:239], off offset:512
	global_load_dword v245, v[238:239], off offset:576
	global_load_dword v246, v[238:239], off offset:640
	global_load_dword v247, v[238:239], off offset:704
.Lmy_rs_skip_next:
.LBB0_192:
	s_add_i32 s63, s63, 1
	s_lshr_b32 s98, s63, 1
	s_lshr_b32 s99, s63, 2
	s_xor_b32 s98, s98, s99
	s_and_b32 s98, s98, 1
	s_mul_i32 s98, s98, 6
	s_xor_b32 s98, s63, s98
	s_and_b32 s99, s2, 1
	s_lshl_b32 s99, s99, 1
	s_xor_b32 s99, s98, s99
	s_mul_i32 s0, s99, s10
	s_add_i32 s0, s0, s2
	s_cmpk_gt_i32 s0, 0x7ff
	s_cselect_b64 s[46:47], -1, 0
	s_and_b64 vcc, exec, s[46:47]
	s_cbranch_vccnz .LBB0_198
	s_ashr_i32 s1, s0, 31
	s_lshr_b32 s1, s1, 29
	s_add_i32 s23, s0, s1
	s_and_b32 s1, s23, -8
	s_sub_i32 s24, s0, s1
	s_cmp_gt_i32 s24, -1
	s_mov_b64 s[0:1], -1
	s_cbranch_scc0 .LBB0_195
	s_lshl_b32 s25, s24, 8
	s_mov_b64 s[0:1], 0

.LBB0_199:
	s_add_u32 s26, s40, s0
	s_addc_u32 s27, s41, s1
	s_add_u32 s26, s26, 0x100
	s_addc_u32 s27, s27, 0
	s_add_u32 s42, s23, s0
	s_addc_u32 s43, s24, s1
	s_add_i32 s49, 0, 0x10000
	v_add_u32_e32 v142, s49, v146
	ds_read_b128 v[148:151], v142
	ds_read_b128 v[152:155], v142 offset:1024
	ds_read_b128 v[156:159], v142 offset:2048
	ds_read_b128 v[160:163], v142 offset:3072
	s_cmpk_eq_i32 s0, 0x700
	s_cselect_b32 s45, s69, s27
	s_cselect_b32 s44, s68, s26
	s_cselect_b32 s43, s35, s43
	s_cselect_b32 s42, s34, s42
	v_lshl_add_u64 v[142:143], v[140:141], 0, s[0:1]
	s_add_i32 m0, s18, 0xc000
	ds_read_b128 v[164:167], v147
	ds_read_b128 v[174:177], v147 offset:1024
	ds_read_b128 v[178:181], v147 offset:2048
	ds_read_b128 v[182:185], v147 offset:3072
	ds_read_b128 v[186:189], v147 offset:4096
	ds_read_b128 v[190:193], v147 offset:5120
	ds_read_b128 v[202:205], v147 offset:6144
	ds_read_b128 v[206:209], v147 offset:7168
	global_load_lds_dwordx4 v[142:143], off
	v_lshl_add_u64 v[142:143], v[138:139], 0, s[0:1]
	s_add_i32 m0, s18, 0xe000
	s_nop 0
	global_load_lds_dwordx4 v[142:143], off
	s_waitcnt lgkmcnt(8)
	s_barrier
	s_waitcnt lgkmcnt(0)
	s_setprio 1
	s_waitcnt lgkmcnt(0)
	v_mfma_f32_16x16x32_bf16 v[124:127], v[148:151], v[164:167], v[124:127]
	v_mfma_f32_16x16x32_bf16 v[120:123], v[156:159], v[164:167], v[120:123]
	v_mfma_f32_16x16x32_bf16 v[108:111], v[148:151], v[178:181], v[108:111]
	v_mfma_f32_16x16x32_bf16 v[104:107], v[156:159], v[178:181], v[104:107]
	v_mfma_f32_16x16x32_bf16 v[92:95], v[148:151], v[186:189], v[92:95]
	v_mfma_f32_16x16x32_bf16 v[88:91], v[156:159], v[186:189], v[88:91]
	v_mfma_f32_16x16x32_bf16 v[76:79], v[148:151], v[202:205], v[76:79]
	v_mfma_f32_16x16x32_bf16 v[72:75], v[156:159], v[202:205], v[72:75]
	v_mfma_f32_16x16x32_bf16 v[124:127], v[152:155], v[174:177], v[124:127]
	v_mfma_f32_16x16x32_bf16 v[120:123], v[160:163], v[174:177], v[120:123]
	v_mfma_f32_16x16x32_bf16 v[108:111], v[152:155], v[182:185], v[108:111]
	v_mfma_f32_16x16x32_bf16 v[104:107], v[160:163], v[182:185], v[104:107]
	v_mfma_f32_16x16x32_bf16 v[92:95], v[152:155], v[190:193], v[92:95]
	v_mfma_f32_16x16x32_bf16 v[88:91], v[160:163], v[190:193], v[88:91]
	v_mfma_f32_16x16x32_bf16 v[76:79], v[152:155], v[206:209], v[76:79]
	v_mfma_f32_16x16x32_bf16 v[72:75], v[160:163], v[206:209], v[72:75]
	s_setprio 0
	s_barrier
	s_add_i32 s71, 0, 0x14000
	v_add_u32_e32 v142, s71, v146
	s_add_i32 s26, s49, s17
	ds_read_b128 v[210:213], v142
	ds_read_b128 v[214:217], v142 offset:1024
	ds_read_b128 v[218:221], v142 offset:2048
	ds_read_b128 v[222:225], v142 offset:3072
	v_lshl_add_u64 v[142:143], s[42:43], 0, v[172:173]
	s_mov_b32 m0, s26
	v_lshl_add_u64 v[226:227], s[42:43], 0, v[132:133]
	global_load_lds_dwordx4 v[142:143], off
	s_add_i32 m0, s26, 0x2000
	s_nop 0
	global_load_lds_dwordx4 v[226:227], off
	s_barrier
	s_waitcnt lgkmcnt(0)
	s_setprio 1
	s_waitcnt lgkmcnt(0)
	v_mfma_f32_16x16x32_bf16 v[116:119], v[210:213], v[164:167], v[116:119]
	v_mfma_f32_16x16x32_bf16 v[112:115], v[218:221], v[164:167], v[112:115]
	v_mfma_f32_16x16x32_bf16 v[100:103], v[210:213], v[178:181], v[100:103]
	v_mfma_f32_16x16x32_bf16 v[96:99], v[218:221], v[178:181], v[96:99]
	v_mfma_f32_16x16x32_bf16 v[84:87], v[210:213], v[186:189], v[84:87]
	v_mfma_f32_16x16x32_bf16 v[80:83], v[218:221], v[186:189], v[80:83]
	v_mfma_f32_16x16x32_bf16 v[68:71], v[210:213], v[202:205], v[68:71]
	v_mfma_f32_16x16x32_bf16 v[64:67], v[218:221], v[202:205], v[64:67]
	v_mfma_f32_16x16x32_bf16 v[116:119], v[214:217], v[174:177], v[116:119]
	v_mfma_f32_16x16x32_bf16 v[112:115], v[222:225], v[174:177], v[112:115]
	v_mfma_f32_16x16x32_bf16 v[100:103], v[214:217], v[182:185], v[100:103]
	v_mfma_f32_16x16x32_bf16 v[96:99], v[222:225], v[182:185], v[96:99]
	v_mfma_f32_16x16x32_bf16 v[84:87], v[214:217], v[190:193], v[84:87]
	v_mfma_f32_16x16x32_bf16 v[80:83], v[222:225], v[190:193], v[80:83]
	v_mfma_f32_16x16x32_bf16 v[68:71], v[214:217], v[206:209], v[68:71]
	v_mfma_f32_16x16x32_bf16 v[64:67], v[222:225], v[206:209], v[64:67]
	s_setprio 0
	s_mov_b32 m0, s18
	v_lshl_add_u64 v[228:229], s[44:45], 0, v[128:129]
	s_barrier
	ds_read_b128 v[164:167], v147 offset:16384
	ds_read_b128 v[174:177], v147 offset:17408
	ds_read_b128 v[178:181], v147 offset:18432
	ds_read_b128 v[182:185], v147 offset:19456
	ds_read_b128 v[186:189], v147 offset:20480
	ds_read_b128 v[190:193], v147 offset:21504
	ds_read_b128 v[202:205], v147 offset:22528
	ds_read_b128 v[206:209], v147 offset:23552
	global_load_lds_dwordx4 v[228:229], off
	v_lshl_add_u64 v[230:231], s[44:45], 0, v[130:131]
	s_mov_b32 m0, s19
	s_nop 0
	global_load_lds_dwordx4 v[230:231], off
	s_barrier
	s_waitcnt lgkmcnt(0)
	s_setprio 1
	s_waitcnt lgkmcnt(0)
	v_mfma_f32_16x16x32_bf16 v[60:63], v[148:151], v[164:167], v[60:63]
	v_mfma_f32_16x16x32_bf16 v[56:59], v[156:159], v[164:167], v[56:59]
	v_mfma_f32_16x16x32_bf16 v[44:47], v[148:151], v[178:181], v[44:47]
	v_mfma_f32_16x16x32_bf16 v[40:43], v[156:159], v[178:181], v[40:43]
	v_mfma_f32_16x16x32_bf16 v[28:31], v[148:151], v[186:189], v[28:31]
	v_mfma_f32_16x16x32_bf16 v[24:27], v[156:159], v[186:189], v[24:27]
	v_mfma_f32_16x16x32_bf16 v[12:15], v[148:151], v[202:205], v[12:15]
	v_mfma_f32_16x16x32_bf16 v[8:11], v[156:159], v[202:205], v[8:11]
	v_mfma_f32_16x16x32_bf16 v[60:63], v[152:155], v[174:177], v[60:63]
	v_mfma_f32_16x16x32_bf16 v[56:59], v[160:163], v[174:177], v[56:59]
	v_mfma_f32_16x16x32_bf16 v[44:47], v[152:155], v[182:185], v[44:47]
	v_mfma_f32_16x16x32_bf16 v[40:43], v[160:163], v[182:185], v[40:43]
	v_mfma_f32_16x16x32_bf16 v[28:31], v[152:155], v[190:193], v[28:31]
	v_mfma_f32_16x16x32_bf16 v[24:27], v[160:163], v[190:193], v[24:27]
	v_mfma_f32_16x16x32_bf16 v[12:15], v[152:155], v[206:209], v[12:15]
	v_mfma_f32_16x16x32_bf16 v[8:11], v[160:163], v[206:209], v[8:11]
	s_setprio 0
	s_barrier
	s_add_u32 s26, s42, 0x40000
	s_addc_u32 s27, s43, 0
	s_add_i32 s49, s71, s17
	v_lshl_add_u64 v[148:149], s[26:27], 0, v[172:173]
	s_mov_b32 m0, s49
	s_nop 0
	global_load_lds_dwordx4 v[148:149], off
	v_lshl_add_u64 v[148:149], s[26:27], 0, v[132:133]
	s_add_i32 m0, s49, 0x2000
	s_nop 0
	global_load_lds_dwordx4 v[148:149], off
	s_waitcnt vmcnt(6)
	s_barrier
	s_setprio 1
	v_mfma_f32_16x16x32_bf16 v[52:55], v[210:213], v[164:167], v[52:55]
	v_mfma_f32_16x16x32_bf16 v[48:51], v[218:221], v[164:167], v[48:51]
	v_mfma_f32_16x16x32_bf16 v[36:39], v[210:213], v[178:181], v[36:39]
	v_mfma_f32_16x16x32_bf16 v[32:35], v[218:221], v[178:181], v[32:35]
	v_mfma_f32_16x16x32_bf16 v[20:23], v[210:213], v[186:189], v[20:23]
	v_mfma_f32_16x16x32_bf16 v[16:19], v[218:221], v[186:189], v[16:19]
	v_mfma_f32_16x16x32_bf16 v[4:7], v[210:213], v[202:205], v[4:7]
	v_mfma_f32_16x16x32_bf16 v[0:3], v[218:221], v[202:205], v[0:3]
	v_mfma_f32_16x16x32_bf16 v[52:55], v[214:217], v[174:177], v[52:55]
	v_mfma_f32_16x16x32_bf16 v[48:51], v[222:225], v[174:177], v[48:51]
	v_mfma_f32_16x16x32_bf16 v[36:39], v[214:217], v[182:185], v[36:39]
	v_mfma_f32_16x16x32_bf16 v[32:35], v[222:225], v[182:185], v[32:35]
	v_mfma_f32_16x16x32_bf16 v[20:23], v[214:217], v[190:193], v[20:23]
	v_mfma_f32_16x16x32_bf16 v[16:19], v[222:225], v[190:193], v[16:19]
	v_mfma_f32_16x16x32_bf16 v[4:7], v[214:217], v[206:209], v[4:7]
	v_mfma_f32_16x16x32_bf16 v[0:3], v[222:225], v[206:209], v[0:3]
	s_setprio 0
	s_add_i32 s49, 0, 0x18000
	v_add_u32_e32 v160, s49, v146
	s_barrier
	ds_read_b128 v[148:151], v160
	ds_read_b128 v[152:155], v160 offset:1024
	ds_read_b128 v[156:159], v160 offset:2048
	ds_read_b128 v[160:163], v160 offset:3072
	s_add_u32 s26, s44, s54
	s_addc_u32 s27, s45, 0
	s_mov_b32 m0, s20
	v_lshl_add_u64 v[210:211], s[26:27], 0, v[128:129]
	ds_read_b128 v[164:167], v147 offset:32768
	ds_read_b128 v[174:177], v147 offset:33792
	ds_read_b128 v[178:181], v147 offset:34816
	ds_read_b128 v[182:185], v147 offset:35840
	ds_read_b128 v[186:189], v147 offset:36864
	ds_read_b128 v[190:193], v147 offset:37888
	ds_read_b128 v[202:205], v147 offset:38912
	ds_read_b128 v[206:209], v147 offset:39936
	global_load_lds_dwordx4 v[210:211], off
	v_lshl_add_u64 v[210:211], s[26:27], 0, v[130:131]
	s_mov_b32 m0, s21
	s_nop 0
	global_load_lds_dwordx4 v[210:211], off
	s_waitcnt lgkmcnt(8)
	s_barrier
	s_waitcnt lgkmcnt(0)
	s_setprio 1
	s_waitcnt lgkmcnt(0)
	v_mfma_f32_16x16x32_bf16 v[124:127], v[148:151], v[164:167], v[124:127]
	v_mfma_f32_16x16x32_bf16 v[120:123], v[156:159], v[164:167], v[120:123]
	v_mfma_f32_16x16x32_bf16 v[108:111], v[148:151], v[178:181], v[108:111]
	v_mfma_f32_16x16x32_bf16 v[104:107], v[156:159], v[178:181], v[104:107]
	v_mfma_f32_16x16x32_bf16 v[92:95], v[148:151], v[186:189], v[92:95]
	v_mfma_f32_16x16x32_bf16 v[88:91], v[156:159], v[186:189], v[88:91]
	v_mfma_f32_16x16x32_bf16 v[76:79], v[148:151], v[202:205], v[76:79]
	v_mfma_f32_16x16x32_bf16 v[72:75], v[156:159], v[202:205], v[72:75]
	v_mfma_f32_16x16x32_bf16 v[124:127], v[152:155], v[174:177], v[124:127]
	v_mfma_f32_16x16x32_bf16 v[120:123], v[160:163], v[174:177], v[120:123]
	v_mfma_f32_16x16x32_bf16 v[108:111], v[152:155], v[182:185], v[108:111]
	v_mfma_f32_16x16x32_bf16 v[104:107], v[160:163], v[182:185], v[104:107]
	v_mfma_f32_16x16x32_bf16 v[92:95], v[152:155], v[190:193], v[92:95]
	v_mfma_f32_16x16x32_bf16 v[88:91], v[160:163], v[190:193], v[88:91]
	v_mfma_f32_16x16x32_bf16 v[76:79], v[152:155], v[206:209], v[76:79]
	v_mfma_f32_16x16x32_bf16 v[72:75], v[160:163], v[206:209], v[72:75]
	s_setprio 0
	s_barrier
	s_add_i32 s44, 0, 0x1c000
	s_add_i32 s26, s49, s17
	v_add_u32_e32 v201, s44, v146
	v_lshl_add_u64 v[142:143], v[142:143], 0, s[76:77]
	s_mov_b32 m0, s26
	ds_read_b128 v[210:213], v201
	ds_read_b128 v[214:217], v201 offset:1024
	ds_read_b128 v[218:221], v201 offset:2048
	ds_read_b128 v[222:225], v201 offset:3072
	global_load_lds_dwordx4 v[142:143], off
	v_lshl_add_u64 v[142:143], v[226:227], 0, s[76:77]
	s_add_i32 m0, s26, 0x2000
	s_nop 0
	global_load_lds_dwordx4 v[142:143], off
	s_barrier
	s_waitcnt lgkmcnt(0)
	s_setprio 1
	s_waitcnt lgkmcnt(0)
	v_mfma_f32_16x16x32_bf16 v[116:119], v[210:213], v[164:167], v[116:119]
	v_mfma_f32_16x16x32_bf16 v[112:115], v[218:221], v[164:167], v[112:115]
	v_mfma_f32_16x16x32_bf16 v[100:103], v[210:213], v[178:181], v[100:103]
	v_mfma_f32_16x16x32_bf16 v[96:99], v[218:221], v[178:181], v[96:99]
	v_mfma_f32_16x16x32_bf16 v[84:87], v[210:213], v[186:189], v[84:87]
	v_mfma_f32_16x16x32_bf16 v[80:83], v[218:221], v[186:189], v[80:83]
	v_mfma_f32_16x16x32_bf16 v[68:71], v[210:213], v[202:205], v[68:71]
	v_mfma_f32_16x16x32_bf16 v[64:67], v[218:221], v[202:205], v[64:67]
	v_mfma_f32_16x16x32_bf16 v[116:119], v[214:217], v[174:177], v[116:119]
	v_mfma_f32_16x16x32_bf16 v[112:115], v[222:225], v[174:177], v[112:115]
	v_mfma_f32_16x16x32_bf16 v[100:103], v[214:217], v[182:185], v[100:103]
	v_mfma_f32_16x16x32_bf16 v[96:99], v[222:225], v[182:185], v[96:99]
	v_mfma_f32_16x16x32_bf16 v[84:87], v[214:217], v[190:193], v[84:87]
	v_mfma_f32_16x16x32_bf16 v[80:83], v[222:225], v[190:193], v[80:83]
	v_mfma_f32_16x16x32_bf16 v[68:71], v[214:217], v[206:209], v[68:71]
	v_mfma_f32_16x16x32_bf16 v[64:67], v[222:225], v[206:209], v[64:67]
	s_setprio 0
	s_mov_b32 m0, s60
	v_lshl_add_u64 v[142:143], v[228:229], 0, s[76:77]
	s_barrier
	ds_read_b128 v[164:167], v147 offset:49152
	ds_read_b128 v[174:177], v147 offset:50176
	ds_read_b128 v[178:181], v147 offset:51200
	ds_read_b128 v[182:185], v147 offset:52224
	ds_read_b128 v[186:189], v147 offset:53248
	ds_read_b128 v[190:193], v147 offset:54272
	ds_read_b128 v[202:205], v147 offset:55296
	ds_read_b128 v[206:209], v147 offset:56320
	global_load_lds_dwordx4 v[142:143], off
	v_lshl_add_u64 v[142:143], v[230:231], 0, s[76:77]
	s_mov_b32 m0, s61
	s_nop 0
	global_load_lds_dwordx4 v[142:143], off
	s_barrier
	s_waitcnt lgkmcnt(0)
	s_setprio 1
	s_waitcnt lgkmcnt(0)
	v_mfma_f32_16x16x32_bf16 v[60:63], v[148:151], v[164:167], v[60:63]
	v_mfma_f32_16x16x32_bf16 v[56:59], v[156:159], v[164:167], v[56:59]
	v_mfma_f32_16x16x32_bf16 v[44:47], v[148:151], v[178:181], v[44:47]
	v_mfma_f32_16x16x32_bf16 v[40:43], v[156:159], v[178:181], v[40:43]
	v_mfma_f32_16x16x32_bf16 v[28:31], v[148:151], v[186:189], v[28:31]
	v_mfma_f32_16x16x32_bf16 v[24:27], v[156:159], v[186:189], v[24:27]
	v_mfma_f32_16x16x32_bf16 v[12:15], v[148:151], v[202:205], v[12:15]
	v_mfma_f32_16x16x32_bf16 v[8:11], v[156:159], v[202:205], v[8:11]
	v_mfma_f32_16x16x32_bf16 v[60:63], v[152:155], v[174:177], v[60:63]
	v_mfma_f32_16x16x32_bf16 v[56:59], v[160:163], v[174:177], v[56:59]
	v_mfma_f32_16x16x32_bf16 v[44:47], v[152:155], v[182:185], v[44:47]
	v_mfma_f32_16x16x32_bf16 v[40:43], v[160:163], v[182:185], v[40:43]
	v_mfma_f32_16x16x32_bf16 v[28:31], v[152:155], v[190:193], v[28:31]
	v_mfma_f32_16x16x32_bf16 v[24:27], v[160:163], v[190:193], v[24:27]
	v_mfma_f32_16x16x32_bf16 v[12:15], v[152:155], v[206:209], v[12:15]
	v_mfma_f32_16x16x32_bf16 v[8:11], v[160:163], v[206:209], v[8:11]
	s_setprio 0
	s_barrier
	s_add_u32 s26, s42, 0x40080
	s_addc_u32 s27, s43, 0
	s_add_i32 s42, s44, s17
	v_lshl_add_u64 v[142:143], s[26:27], 0, v[172:173]
	s_mov_b32 m0, s42
	s_nop 0
	global_load_lds_dwordx4 v[142:143], off
	v_lshl_add_u64 v[142:143], s[26:27], 0, v[132:133]
	s_add_i32 m0, s42, 0x2000
	s_nop 0
	global_load_lds_dwordx4 v[142:143], off
	s_waitcnt vmcnt(6)
	s_barrier
	s_setprio 1
	v_mfma_f32_16x16x32_bf16 v[52:55], v[210:213], v[164:167], v[52:55]
	v_mfma_f32_16x16x32_bf16 v[48:51], v[218:221], v[164:167], v[48:51]
	v_mfma_f32_16x16x32_bf16 v[36:39], v[210:213], v[178:181], v[36:39]
	v_mfma_f32_16x16x32_bf16 v[32:35], v[218:221], v[178:181], v[32:35]
	v_mfma_f32_16x16x32_bf16 v[20:23], v[210:213], v[186:189], v[20:23]
	v_mfma_f32_16x16x32_bf16 v[16:19], v[218:221], v[186:189], v[16:19]
	v_mfma_f32_16x16x32_bf16 v[4:7], v[210:213], v[202:205], v[4:7]
	v_mfma_f32_16x16x32_bf16 v[0:3], v[218:221], v[202:205], v[0:3]
	v_mfma_f32_16x16x32_bf16 v[52:55], v[214:217], v[174:177], v[52:55]
	v_mfma_f32_16x16x32_bf16 v[48:51], v[222:225], v[174:177], v[48:51]
	v_mfma_f32_16x16x32_bf16 v[36:39], v[214:217], v[182:185], v[36:39]
	v_mfma_f32_16x16x32_bf16 v[32:35], v[222:225], v[182:185], v[32:35]
	v_mfma_f32_16x16x32_bf16 v[20:23], v[214:217], v[190:193], v[20:23]
	v_mfma_f32_16x16x32_bf16 v[16:19], v[222:225], v[190:193], v[16:19]
	v_mfma_f32_16x16x32_bf16 v[4:7], v[214:217], v[206:209], v[4:7]
	v_mfma_f32_16x16x32_bf16 v[0:3], v[222:225], v[206:209], v[0:3]
	s_setprio 0
	s_add_i32 s25, s25, 2
	s_add_u32 s0, s0, 0x100
	s_addc_u32 s1, s1, 0
	s_cmp_gt_u32 s25, 13
	s_barrier
	s_cbranch_scc0 .LBB0_199
	v_mov_b32_e32 v138, v144
	v_mov_b32_e32 v140, v145
	s_lshl_b32 s0, s22, 8
	s_add_i32 s0, s0, s59
	v_add_u32_e32 v138, s0, v138
	v_cndmask_b32_e64 v141, 0, 1, s[78:79]
	v_ashrrev_i32_e32 v139, 31, v138
	v_cmp_ne_u32_e64 s[42:43], 1, v141
	s_andn2_b64 vcc, exec, s[78:79]
	v_mov_b32_e32 v150, 1.0
	s_cbranch_vccnz .LBB0_202
	v_lshl_add_u64 v[142:143], v[138:139], 2, s[64:65]
	v_fmamk_f32 v139, v240, 0x3a800000, v197
	s_nop 0
	s_nop 0
	s_nop 0
	s_nop 0
	s_nop 0
	s_nop 0
	s_nop 0
	s_nop 0
	s_nop 0
	s_nop 0
	s_nop 0
	s_nop 0
	s_nop 0
	s_nop 0
	s_nop 0
	s_nop 0
	s_nop 0
	v_rsq_f32_e32 v150, v139

.LBB0_206:
	s_nop 1
	v_add_u32_e32 v112, 16, v138
	v_ashrrev_i32_e32 v113, 31, v112
	s_and_b64 vcc, exec, s[42:43]
	v_mov_b32_e32 v117, 1.0
	s_cbranch_vccnz .LBB0_208
	v_fmamk_f32 v113, v241, 0x3a800000, v197
	v_rsq_f32_e32 v117, v113

.LBB0_212:
	s_nop 1
	v_add_u32_e32 v96, 32, v138
	v_readlane_b32 s52, v234, 52
	v_readlane_b32 s78, v234, 57
	v_ashrrev_i32_e32 v97, 31, v96
	s_and_b64 vcc, exec, s[42:43]
	v_mov_b32_e32 v101, 1.0
	v_readlane_b32 s53, v234, 53
	v_readlane_b32 s79, v234, 58
	s_cbranch_vccnz .LBB0_214
	v_fmamk_f32 v97, v242, 0x3a800000, v197
	v_rsq_f32_e32 v101, v97

.LBB0_218:
	s_nop 1
	v_add_u32_e32 v80, 48, v138
	v_ashrrev_i32_e32 v81, 31, v80
	s_and_b64 vcc, exec, s[42:43]
	v_mov_b32_e32 v85, 1.0
	s_cbranch_vccnz .LBB0_220
	v_fmamk_f32 v81, v243, 0x3a800000, v197
	v_rsq_f32_e32 v85, v81

.LBB0_224:
	s_nop 1
	v_add_u32_e32 v64, 0x80, v138
	v_ashrrev_i32_e32 v65, 31, v64
	s_and_b64 vcc, exec, s[42:43]
	v_mov_b32_e32 v69, 1.0
	s_cbranch_vccnz .LBB0_226
	v_fmamk_f32 v65, v244, 0x3a800000, v197
	v_rsq_f32_e32 v69, v65

.LBB0_230:
	s_nop 1
	v_add_u32_e32 v48, 0x90, v138
	v_ashrrev_i32_e32 v49, 31, v48
	s_and_b64 vcc, exec, s[42:43]
	v_mov_b32_e32 v53, 1.0
	s_cbranch_vccnz .LBB0_232
	v_fmamk_f32 v49, v245, 0x3a800000, v197
	v_rsq_f32_e32 v53, v49

.LBB0_236:
	s_nop 1
	v_add_u32_e32 v32, 0xa0, v138
	v_ashrrev_i32_e32 v33, 31, v32
	s_and_b64 vcc, exec, s[42:43]
	v_mov_b32_e32 v37, 1.0
	s_cbranch_vccnz .LBB0_238
	v_fmamk_f32 v33, v246, 0x3a800000, v197
	v_rsq_f32_e32 v37, v33

.LBB0_242:
	s_nop 1
	v_add_u32_e32 v16, 0xb0, v138
	v_ashrrev_i32_e32 v17, 31, v16
	s_and_b64 vcc, exec, s[42:43]
	v_mov_b32_e32 v21, 1.0
	s_cbranch_vccnz .LBB0_244
	v_fmamk_f32 v17, v247, 0x3a800000, v197
	v_rsq_f32_e32 v21, v17
